# static s_setprio 1 for waves 0-3 (the leading ping-pong half) for the whole kernel, no per-segment toggles
# baseline (speedup 1.0000x reference)
; __global__ void __launch_bounds__(512, 2) fwd_megakernel(Params p) {
;   extern __shared__ __attribute__((aligned(16))) unsigned char dsm[];
;   char* smem = (char*)dsm;
;   cg::grid_group grid = cg::this_grid();
;   if (threadIdx.x == 0) *(uint4*)(dsm + 131072) = make_uint4(0u, 0u, 0u, 0u);
;   __syncthreads();
_Z14fwd_megakernel6Params:
	s_load_dwordx4 s[56:59], s[0:1], 0xe0
	s_load_dwordx8 s[60:67], s[0:1], 0xc0
	s_mov_b32 s54, s2
	s_add_u32 s2, s0, 0xf0
	v_and_b32_e32 v213, 0x3ff, v0
	s_addc_u32 s3, s1, 0
	v_cmp_eq_u32_e64 s[68:69], 0, v213
	v_readfirstlane_b32 s4, v213
	s_cmpk_gt_u32 s4, 0xff
	s_cbranch_scc1 .Lprio_skip
	s_setprio 1
.Lprio_skip:
	s_and_saveexec_b64 s[4:5], s[68:69]
	s_cbranch_execz .LBB0_2
	s_add_i32 s6, 16, 0x20000
	v_mov_b32_e32 v2, 0
	v_mov_b32_e32 v3, v2
	v_mov_b32_e32 v4, v2
	v_mov_b32_e32 v5, v2
	v_mov_b32_e32 v1, s6
	ds_write_b128 v1, v[2:5]
